# attention: wave halves staggered by half a tile step (H1 runs softmax+PV of tile t-1 before QK of tile t, second barrier), no setprio
# baseline (speedup 1.0000x reference)
; __device__ __forceinline__ void attn_phase(const Params& p, LAS unsigned char* lds) {
;     ...
;     int tid_ = threadIdx.x; asm volatile("" : "+v"(tid_));
;     const int tid = tid_, lane = tid & 63, wid = tid >> 6, c = lane & 31, hi = lane >> 5;
;     const float NEG = -__builtin_inff();
;     const int srow = tid >> 3, ssub = tid & 7;
;     const int G_ = gridDim.x, vcu = (G_ % 8 == 0) ? (int)(blockIdx.x & 7) * (G_ >> 3) + (int)(blockIdx.x >> 3) : (int)blockIdx.x;
;     for (int it = vcu; it < NBATCH * 8 * 4; it += G_) {
;         const int bh = it >> 2, pp = it & 3, b = bh >> 3, h = bh & 7;
;         for (int half = 0; half < 2; ++half) {
;             const int qblk = half ? 7 - pp : pp;
;             const int tq = qblk * 256 + wid * 32 + c;
;             const size_t rowq = (size_t)b * SEQ + tq;
.LBB0_630:
	s_or_b64 exec, exec, s[0:1]
	v_readfirstlane_b32 s99, v201
	s_nop 3
	s_lshr_b32 s99, s99, 8
	s_and_b32 s0, s30, 7
	s_waitcnt lgkmcnt(0)
	v_mov_b32_e32 v0, v201
	s_cmp_lg_u32 s0, 0
	s_mov_b32 s3, s2
	s_barrier
	s_cbranch_scc0 .LBB0_632
	s_cmpk_gt_i32 s3, 0x3ff
	s_cbranch_scc0 .LBB0_633
	s_branch .LBB0_652

; #define LAS __attribute__((address_space(3)))
; __device__ __forceinline__ void attn_phase(const Params& p, LAS unsigned char* lds) {
;     ...
;             for (int jt = 0; jt < ntiles; ++jt) {
;                 LAS unsigned char* Ks = lds + (jt & 1) * ABUF; LAS unsigned char* Vs = Ks + KBUF;
;                 { LAS unsigned char* kd = Ks + srow * KS_STRIDE + ssub * 16; LAS unsigned char* vd = Vs + srow * VS_STRIDE + ssub * 16;
;                   *(LAS u32x4*)(kd) = kreg[0]; *(LAS u32x4*)(kd + 128) = kreg[1]; *(LAS u32x4*)(kd + 256) = kreg[2]; *(LAS u32x4*)(vd) = vreg[0]; *(LAS u32x4*)(vd + 128) = vreg[1]; }
;                 __syncthreads();
;                 if (jt + 1 < ntiles) LOAD_TILE(jt + 1);
;                 __builtin_amdgcn_sched_barrier(0);
;                 f32x16 p0 = (f32x16){}, p1 = (f32x16){};
;                 { const LAS unsigned char* kp = Ks + c * KS_STRIDE + hi * 16;
;                   bf16x8 a0 = *(const LAS bf16x8*)(kp), a1 = *(const LAS bf16x8*)(kp + 32 * KS_STRIDE);
; #pragma unroll
;                   for (int d = 0; d < 12; ++d) { bf16x8 n0 = a0, n1 = a1;
;                       if (d < 11) { n0 = *(const LAS bf16x8*)(kp + (d + 1) * 32); n1 = *(const LAS bf16x8*)(kp + 32 * KS_STRIDE + (d + 1) * 32); }
;                       p0 = __builtin_amdgcn_mfma_f32_32x32x16_bf16(a0, qf[d], p0, 0, 0, 0); p1 = __builtin_amdgcn_mfma_f32_32x32x16_bf16(a1, qf[d], p1, 0, 0, 0);
;                       a0 = n0; a1 = n1; } }
;                 const LAS unsigned char* vb = Vs + (4 * hi + ((lane & 15) >> 2)) * VS_STRIDE + (((lane >> 4) & 1) * 16 + 4 * (lane & 3)) * 2;
;                 s16x4 vlo[2][4], vhi[2][4];
; #pragma unroll
;                 for (int s = 0; s < 4; ++s) { vlo[0][s] = vtr(vb + (16 * s) * VS_STRIDE); vhi[0][s] = vtr(vb + (16 * s + 8) * VS_STRIDE); }
;                 if (jt == 0) {
; #pragma unroll
;                     for (int r = 0; r < 16; ++r) { if (crow(r, hi) >= NMETA) p0[r] = NEG; p1[r] = NEG; }
;                 } else if (jt - 1 >= 4 * qblk) {
;                     const int kb = 64 * (jt - 1);
; #pragma unroll
;                     for (int r = 0; r < 16; ++r) { const int key = kb + crow(r, hi); if (key > tq) p0[r] = NEG; if (key + 32 > tq) p1[r] = NEG; }
;                 }
;                 float rm = p0[0];
; #pragma unroll
;                 for (int r = 1; r < 16; ++r) rm = fmaxf(rm, p0[r]);
; #pragma unroll
.LBB0_641:
	s_or_b64 exec, exec, s[42:43]
	s_lshl_b32 s50, s50, 2
	s_xor_b64 s[42:43], s[44:45], -1
	s_mov_b32 s8, 2
	s_add_i32 s51, s50, 5
	ds_read_b128 v[0:3], v243
	ds_read_b128 v[16:19], v243 offset:32
	s_mov_b32 s53, 0
	v_mov_b64_e32 v[232:233], v[222:223]
	s_waitcnt lgkmcnt(1)
	v_mfma_f32_32x32x16_bf16 v[0:15], v[0:3], v[96:99], 0
	s_waitcnt lgkmcnt(0)
	v_mfma_f32_32x32x16_bf16 v[0:15], v[16:19], v[100:103], v[0:15]
	ds_read_b128 v[16:19], v243 offset:64
	ds_read_b128 v[20:23], v243 offset:96
	s_waitcnt lgkmcnt(1)
	v_mfma_f32_32x32x16_bf16 v[0:15], v[16:19], v[104:107], v[0:15]
	s_waitcnt lgkmcnt(0)
	v_mfma_f32_32x32x16_bf16 v[0:15], v[20:23], v[108:111], v[0:15]
	ds_read_b128 v[16:19], v243 offset:128
	ds_read_b128 v[20:23], v243 offset:160
	s_waitcnt lgkmcnt(1)
	v_mfma_f32_32x32x16_bf16 v[0:15], v[16:19], v[112:115], v[0:15]
	s_waitcnt lgkmcnt(0)
	v_mfma_f32_32x32x16_bf16 v[0:15], v[20:23], v[116:119], v[0:15]
	ds_read_b128 v[16:19], v243 offset:192
	ds_read_b128 v[20:23], v243 offset:224
	s_waitcnt lgkmcnt(1)
	v_mfma_f32_32x32x16_bf16 v[0:15], v[16:19], v[120:123], v[0:15]
	s_waitcnt lgkmcnt(0)
	v_mfma_f32_32x32x16_bf16 v[0:15], v[20:23], v[124:127], v[0:15]
	ds_read_b128 v[16:19], v243 offset:256
	ds_read_b128 v[20:23], v243 offset:288
	s_waitcnt lgkmcnt(1)
	v_mfma_f32_32x32x16_bf16 v[0:15], v[16:19], v[128:131], v[0:15]
	s_waitcnt lgkmcnt(0)
	v_mfma_f32_32x32x16_bf16 v[0:15], v[20:23], v[132:135], v[0:15]
	ds_read_b128 v[16:19], v243 offset:320
	ds_read_b128 v[20:23], v243 offset:352
	s_waitcnt lgkmcnt(1)
	v_mfma_f32_32x32x16_bf16 v[0:15], v[16:19], v[136:139], v[0:15]
	ds_read_b64_tr_b16 v[16:17], v244 offset:25600
	ds_read_b64_tr_b16 v[24:25], v244 offset:25664
	ds_read_b64_tr_b16 v[64:65], v244 offset:25728
	ds_read_b64_tr_b16 v[68:69], v244 offset:25792
	ds_read_b64_tr_b16 v[18:19], v244 offset:28160
	ds_read_b64_tr_b16 v[26:27], v244 offset:28224
	ds_read_b64_tr_b16 v[66:67], v244 offset:28288
	ds_read_b64_tr_b16 v[70:71], v244 offset:28352
	s_waitcnt lgkmcnt(8)
	v_mfma_f32_32x32x16_bf16 v[0:15], v[20:23], v[140:143], v[0:15]
	s_nop 11
	v_max3_f32 v8, v0, v1, v2
	v_max3_f32 v8, v8, v3, v4
	v_max3_f32 v8, v8, v5, v6
	v_max3_f32 v8, v8, v7, s46
	ds_bpermute_b32 v9, v241, v8
	s_waitcnt lgkmcnt(0)
	v_max3_f32 v182, v8, v9, s47
	v_sub_f32_e32 v8, 0xf149f2ca, v182
	v_exp_f32_e32 v176, v8
	v_sub_f32_e32 v0, v0, v182
	v_sub_f32_e32 v1, v1, v182
	v_sub_f32_e32 v2, v2, v182
	v_sub_f32_e32 v3, v3, v182
	v_sub_f32_e32 v4, v4, v182
	v_sub_f32_e32 v5, v5, v182
	v_sub_f32_e32 v6, v6, v182
	v_sub_f32_e32 v7, v7, v182
	v_exp_f32_e32 v177, v0
	v_exp_f32_e32 v178, v1
	v_exp_f32_e32 v179, v2
	v_exp_f32_e32 v229, v3
	v_exp_f32_e32 v230, v4
	v_exp_f32_e32 v173, v5
	v_exp_f32_e32 v172, v6
	v_exp_f32_e32 v175, v7
	v_cmp_neq_f32_e32 vcc, 1.0, v176
	s_cmp_lg_u64 vcc, 0
	v_mul_f32_e32 v0, 0, v176
	s_cselect_b64 vcc, -1, 0
	v_cndmask_b32_e32 v0, 0, v0, vcc
	v_cvt_pk_bf16_f32 v72, v177, v178
	v_cvt_pk_bf16_f32 v73, v179, v229
	v_cvt_pk_bf16_f32 v74, v230, v173
	v_cvt_pk_bf16_f32 v75, v172, v175
	v_mov_b32_e32 v1, v0
	v_mov_b32_e32 v2, v0
	v_mov_b32_e32 v3, v0
	v_mov_b32_e32 v4, v0
	v_mov_b32_e32 v5, v0
	v_mov_b32_e32 v6, v0
	v_mov_b32_e32 v7, v0
	v_mov_b32_e32 v8, v0
	v_mov_b32_e32 v9, v0
	v_mov_b32_e32 v10, v0
	v_mov_b32_e32 v11, v0
	v_mov_b32_e32 v12, v0
	v_mov_b32_e32 v13, v0
	v_mov_b32_e32 v14, v0
	v_mov_b32_e32 v15, v0
	v_sub_f32_e32 v22, 0xff800000, v182
	v_exp_f32_e32 v174, v22
	v_mfma_f32_32x32x16_bf16 v[48:63], v[16:19], v[72:75], v[0:15]
	ds_read_b64_tr_b16 v[18:19], v244 offset:33280
	ds_read_b64_tr_b16 v[16:17], v244 offset:30720
	ds_read_b64_tr_b16 v[20:21], v244 offset:30784
	ds_read_b64_tr_b16 v[76:77], v244 offset:30848
	ds_read_b64_tr_b16 v[80:81], v244 offset:30912
	ds_read_b64_tr_b16 v[22:23], v244 offset:33344
	ds_read_b64_tr_b16 v[78:79], v244 offset:33408
	ds_read_b64_tr_b16 v[82:83], v244 offset:33472
	v_cvt_pk_bf16_f32 v84, v174, v174
	v_mov_b32_e32 v85, v84
	v_mov_b32_e32 v86, v84
	v_mov_b32_e32 v87, v84
	s_addk_i32 s52, 0x100
	v_mfma_f32_32x32x16_bf16 v[32:47], v[24:27], v[72:75], v[0:15]
	s_waitcnt lgkmcnt(6)
	v_mfma_f32_32x32x16_bf16 v[48:63], v[16:19], v[84:87], v[48:63]
	ds_read_b64_tr_b16 v[16:17], v244 offset:35840
	ds_read_b64_tr_b16 v[18:19], v244 offset:38400
	s_waitcnt lgkmcnt(4)
	v_mfma_f32_32x32x16_bf16 v[32:47], v[20:23], v[84:87], v[32:47]
	ds_read_b64_tr_b16 v[20:21], v244 offset:43520
	ds_read_b64_tr_b16 v[22:23], v244 offset:35904
	ds_read_b64_tr_b16 v[88:89], v244 offset:35968
	ds_read_b64_tr_b16 v[92:93], v244 offset:36032
	ds_read_b64_tr_b16 v[24:25], v244 offset:38464
	ds_read_b64_tr_b16 v[90:91], v244 offset:38528
	ds_read_b64_tr_b16 v[94:95], v244 offset:38592
	s_waitcnt lgkmcnt(7)
	v_mfma_f32_32x32x16_bf16 v[48:63], v[16:19], v[84:87], v[48:63]
	ds_read_b64_tr_b16 v[18:19], v244 offset:40960
	ds_read_b64_tr_b16 v[26:27], v244 offset:41024
	ds_read_b64_tr_b16 v[164:165], v244 offset:41088
	ds_read_b64_tr_b16 v[168:169], v244 offset:41152
	ds_read_b64_tr_b16 v[28:29], v244 offset:43584
	ds_read_b64_tr_b16 v[166:167], v244 offset:43648
	ds_read_b64_tr_b16 v[170:171], v244 offset:43712
	s_waitcnt lgkmcnt(9)
	v_mfma_f32_32x32x16_bf16 v[32:47], v[22:25], v[84:87], v[32:47]
	s_waitcnt lgkmcnt(6)
	v_mfma_f32_32x32x16_bf16 v[48:63], v[18:21], v[84:87], v[48:63]
	s_waitcnt lgkmcnt(2)
	v_mfma_f32_32x32x16_bf16 v[32:47], v[26:29], v[84:87], v[32:47]
	v_mfma_f32_32x32x16_bf16 v[16:31], v[64:67], v[72:75], v[0:15]
	v_add_f32_e32 v64, v177, v174
	v_add_f32_e32 v64, 0, v64
	v_add_f32_e32 v65, v178, v174
	v_add_f32_e32 v64, v65, v64
	v_add_f32_e32 v65, v179, v174
	v_add_f32_e32 v64, v65, v64
	v_add_f32_e32 v65, v229, v174
	v_mfma_f32_32x32x16_bf16 v[0:15], v[68:71], v[72:75], v[0:15]
	v_add_f32_e32 v64, v65, v64
	v_add_f32_e32 v65, v230, v174
	v_add_f32_e32 v66, v65, v64
	v_add_f32_e64 v64, v172, v174
	v_add_f32_e64 v65, v173, v174
	v_mov_b64_e32 v[230:231], v[224:225]
	v_add_f32_e32 v65, v65, v66
	v_add_f32_e32 v66, v64, v65
	v_mfma_f32_32x32x16_bf16 v[16:31], v[76:79], v[84:87], v[16:31]
	v_add_f32_e64 v64, v174, v174
	v_add_f32_e64 v65, v175, v174
	v_add_f32_e32 v65, v65, v66
	v_add_f32_e32 v65, v64, v65
	v_add_f32_e32 v65, v64, v65
	v_add_f32_e32 v65, v64, v65
	v_add_f32_e32 v65, v64, v65
	v_mfma_f32_32x32x16_bf16 v[0:15], v[80:83], v[84:87], v[0:15]
	v_add_f32_e32 v65, v64, v65
	v_add_f32_e32 v65, v64, v65
	v_add_f32_e32 v65, v64, v65
	v_add_f32_e32 v229, v64, v65
	v_fmac_f32_e32 v229, 0, v176
	v_mfma_f32_32x32x16_bf16 v[16:31], v[88:91], v[84:87], v[16:31]
	v_mfma_f32_32x32x16_bf16 v[0:15], v[92:95], v[84:87], v[0:15]
	s_waitcnt lgkmcnt(1)
	v_mfma_f32_32x32x16_bf16 v[16:31], v[164:167], v[84:87], v[16:31]
	s_waitcnt lgkmcnt(0)
	v_mfma_f32_32x32x16_bf16 v[0:15], v[168:171], v[84:87], v[0:15]
	s_cmp_lg_u32 s99, 0
	s_cbranch_scc1 .Lat1_entry

; __device__ __forceinline__ unsigned cvtpk(float lo, float hi) { return pg8::cvt_pk_bf16(lo, hi); }
; __device__ __forceinline__ s16x4 vtr(const LAS unsigned char* ptr) { return __builtin_bit_cast(s16x4, __builtin_amdgcn_ds_read_tr16_b64_v4i16((LAS v4i16_t*)ptr)); }
; __device__ __forceinline__ void attn_phase(const Params& p, LAS unsigned char* lds) {
;     ...
;                 float rm = p0[0];
; #pragma unroll
;                 for (int r = 1; r < 16; ++r) rm = fmaxf(rm, p0[r]);
; #pragma unroll
;                 for (int r = 0; r < 16; ++r) rm = fmaxf(rm, p1[r]);
;                 rm = fmaxf(rm, __shfl_xor(rm, 32));
;                 const float mn = fmaxf(mrun, rm), alpha = __builtin_amdgcn_exp2f(mrun - mn); mrun = mn;
;                 float ps = 0.f;
; #pragma unroll
;                 for (int r = 0; r < 16; ++r) { p0[r] = __builtin_amdgcn_exp2f(p0[r] - mn); p1[r] = __builtin_amdgcn_exp2f(p1[r] - mn); ps += p0[r] + p1[r]; }
;                 lrun = lrun * alpha + ps;
;                 if (__any(alpha != 1.0f)) {
; #pragma unroll
;                     for (int d = 0; d < 4; ++d) o[d] *= alpha; }
;                 bf16x8 pf[4];
; #pragma unroll
;                 for (int s = 0; s < 2; ++s) {
;                     u32x4 w0 = {cvtpk(p0[8 * s + 0], p0[8 * s + 1]), cvtpk(p0[8 * s + 2], p0[8 * s + 3]), cvtpk(p0[8 * s + 4], p0[8 * s + 5]), cvtpk(p0[8 * s + 6], p0[8 * s + 7])};
;                     u32x4 w1 = {cvtpk(p1[8 * s + 0], p1[8 * s + 1]), cvtpk(p1[8 * s + 2], p1[8 * s + 3]), cvtpk(p1[8 * s + 4], p1[8 * s + 5]), cvtpk(p1[8 * s + 6], p1[8 * s + 7])};
;                     pf[s] = __builtin_bit_cast(bf16x8, w0); pf[2 + s] = __builtin_bit_cast(bf16x8, w1); }
; #pragma unroll
;                 for (int d = 0; d < 4; ++d) {
;                     if (d < 3) {
; #pragma unroll
;                         for (int s = 0; s < 4; ++s) { vlo[(d + 1) & 1][s] = vtr(vb + (16 * s) * VS_STRIDE + (d + 1) * 64); vhi[(d + 1) & 1][s] = vtr(vb + (16 * s + 8) * VS_STRIDE + (d + 1) * 64); } }
; #pragma unroll
;                     for (int s = 0; s < 4; ++s) {
;                         const s16x4 lo = vlo[d & 1][s], hh = vhi[d & 1][s];
;                         const bf16x8 vf = {lo[0], lo[1], lo[2], lo[3], hh[0], hh[1], hh[2], hh[3]};
;                         o[d] = __builtin_amdgcn_mfma_f32_32x32x16_bf16(vf, pf[s], o[d], 0, 0, 0); } }
.LBB0_650:
	v_sub_f32_e32 v64, v64, v246
	v_sub_f32_e32 v80, v80, v246
	v_exp_f32_e32 v64, v64
	v_exp_f32_e32 v80, v80
	v_sub_f32_e32 v65, v65, v246
	v_sub_f32_e32 v81, v81, v246
	v_exp_f32_e32 v65, v65
	v_exp_f32_e32 v81, v81
	v_sub_f32_e32 v66, v66, v246
	v_sub_f32_e32 v82, v82, v246
	v_exp_f32_e32 v66, v66
	v_exp_f32_e32 v82, v82
	v_sub_f32_e32 v67, v67, v246
	v_sub_f32_e32 v83, v83, v246
	v_exp_f32_e32 v67, v67
	v_exp_f32_e32 v83, v83
	v_add_f32_e32 v248, v64, v80
	v_add_f32_e32 v248, 0, v248
	v_add_f32_e32 v249, v65, v81
	v_add_f32_e32 v248, v249, v248
	v_add_f32_e32 v249, v66, v82
	v_add_f32_e32 v248, v249, v248
	v_add_f32_e32 v249, v67, v83
	v_sub_f32_e32 v68, v68, v246
	v_sub_f32_e32 v84, v84, v246
	v_add_f32_e32 v248, v249, v248
	v_exp_f32_e32 v68, v68
	v_exp_f32_e32 v249, v84
	v_sub_f32_e32 v69, v69, v246
	v_sub_f32_e32 v85, v85, v246
	v_exp_f32_e32 v69, v69
	v_exp_f32_e32 v85, v85
	v_sub_f32_e32 v70, v70, v246
	v_sub_f32_e32 v86, v86, v246
	v_exp_f32_e32 v70, v70
	v_exp_f32_e32 v86, v86
	v_sub_f32_e32 v71, v71, v246
	v_sub_f32_e32 v87, v87, v246
	v_exp_f32_e32 v71, v71
	v_exp_f32_e32 v87, v87
	v_sub_f32_e32 v72, v72, v246
	v_sub_f32_e32 v88, v88, v246
	v_add_f32_e32 v84, v68, v249
	v_exp_f32_e32 v72, v72
	v_exp_f32_e32 v88, v88
	v_sub_f32_e32 v73, v73, v246
	v_sub_f32_e32 v89, v89, v246
	v_add_f32_e32 v84, v84, v248
	v_add_f32_e32 v248, v69, v85
	v_exp_f32_e32 v73, v73
	v_exp_f32_e32 v89, v89
	v_sub_f32_e32 v74, v74, v246
	v_sub_f32_e32 v90, v90, v246
	v_add_f32_e32 v84, v248, v84
	v_add_f32_e32 v248, v70, v86
	v_exp_f32_e32 v74, v74
	v_exp_f32_e32 v90, v90
	v_sub_f32_e32 v75, v75, v246
	v_sub_f32_e32 v91, v91, v246
	v_add_f32_e32 v84, v248, v84
	v_add_f32_e32 v248, v71, v87
	v_exp_f32_e32 v75, v75
	v_exp_f32_e32 v91, v91
	v_add_f32_e32 v84, v248, v84
	v_add_f32_e32 v248, v72, v88
	v_add_f32_e32 v84, v248, v84
	v_add_f32_e32 v248, v73, v89
	v_add_f32_e32 v84, v248, v84
	v_add_f32_e32 v248, v74, v90
	v_add_f32_e32 v84, v248, v84
	v_add_f32_e32 v248, v75, v91
	v_sub_f32_e32 v76, v76, v246
	v_add_f32_e32 v84, v248, v84
	v_exp_f32_e32 v248, v76
	v_sub_f32_e32 v76, v92, v246
	v_sub_f32_e32 v77, v77, v246
	v_exp_f32_e32 v92, v76
	v_exp_f32_e32 v250, v77
	v_sub_f32_e32 v77, v93, v246
	v_exp_f32_e32 v93, v77
	v_add_f32_e32 v76, v248, v92
	v_add_f32_e32 v76, v76, v84
	v_cvt_pk_bf16_f32 v72, v72, v73
	v_add_f32_e32 v77, v250, v93
	v_add_f32_e32 v76, v77, v76
	v_sub_f32_e32 v77, v78, v246
	v_exp_f32_e32 v251, v77
	v_sub_f32_e32 v77, v94, v246
	v_exp_f32_e32 v94, v77
	v_cvt_pk_bf16_f32 v78, v68, v69
	v_cvt_pk_bf16_f32 v68, v80, v81
	v_cvt_pk_bf16_f32 v69, v82, v83
	v_add_f32_e32 v77, v251, v94
	v_add_f32_e32 v76, v77, v76
	v_sub_f32_e32 v77, v79, v246
	v_exp_f32_e32 v252, v77
	v_sub_f32_e32 v77, v95, v246
	v_exp_f32_e32 v95, v77
	v_cvt_pk_bf16_f32 v79, v70, v71
	v_cvt_pk_bf16_f32 v70, v249, v85
	v_cvt_pk_bf16_f32 v71, v86, v87
	v_add_f32_e32 v77, v252, v95
	v_add_f32_e32 v84, v77, v76
	v_cvt_pk_bf16_f32 v76, v64, v65
	v_cvt_pk_bf16_f32 v77, v66, v67
	v_cvt_pk_bf16_f32 v73, v74, v75
	v_cvt_pk_bf16_f32 v74, v248, v250
	v_cvt_pk_bf16_f32 v75, v251, v252
	v_cvt_pk_bf16_f32 v64, v88, v89
	v_cvt_pk_bf16_f32 v65, v90, v91
	v_cvt_pk_bf16_f32 v66, v92, v93
	s_barrier
	ds_read_b64_tr_b16 v[80:81], v247 offset:25664
	ds_read_b64_tr_b16 v[82:83], v247 offset:28224
	ds_read_b64_tr_b16 v[86:87], v247 offset:30784
	ds_read_b64_tr_b16 v[88:89], v247 offset:33344
	ds_read_b64_tr_b16 v[90:91], v247 offset:35904
	ds_read_b64_tr_b16 v[92:93], v247 offset:38464
	ds_read_b64_tr_b16 v[248:249], v247 offset:41024
	ds_read_b64_tr_b16 v[250:251], v247 offset:43584
	v_mfma_f32_32x32x16_bf16 v[48:63], v[176:179], v[76:79], v[48:63]
	v_cvt_pk_bf16_f32 v67, v94, v95
	s_add_i32 s53, s53, 64
	s_add_i32 s8, s8, 1
	v_fmac_f32_e32 v84, v229, v182
	v_lshl_add_u64 v[232:233], v[232:233], 0, s[10:11]
	v_lshl_add_u64 v[230:231], v[230:231], 0, s[12:13]
	s_cmp_eq_u32 s52, s53
	s_waitcnt lgkmcnt(6)
	v_mfma_f32_32x32x16_bf16 v[32:47], v[80:83], v[76:79], v[32:47]
	v_mfma_f32_32x32x16_bf16 v[48:63], v[172:175], v[72:75], v[48:63]
	s_waitcnt lgkmcnt(4)
	v_mfma_f32_32x32x16_bf16 v[32:47], v[86:89], v[72:75], v[32:47]
	v_mfma_f32_32x32x16_bf16 v[48:63], v[168:171], v[68:71], v[48:63]
	s_waitcnt lgkmcnt(2)
	v_mfma_f32_32x32x16_bf16 v[32:47], v[90:93], v[68:71], v[32:47]
	v_mfma_f32_32x32x16_bf16 v[48:63], v[164:167], v[64:67], v[48:63]
	ds_read_b64_tr_b16 v[164:165], v247 offset:25728
	ds_read_b64_tr_b16 v[166:167], v247 offset:28288
	ds_read_b64_tr_b16 v[168:169], v247 offset:30848
	ds_read_b64_tr_b16 v[170:171], v247 offset:33408
	ds_read_b64_tr_b16 v[172:173], v247 offset:35968
	ds_read_b64_tr_b16 v[174:175], v247 offset:38528
	ds_read_b64_tr_b16 v[176:177], v247 offset:41088
	ds_read_b64_tr_b16 v[178:179], v247 offset:43648
	s_waitcnt lgkmcnt(8)
	v_mfma_f32_32x32x16_bf16 v[32:47], v[248:251], v[64:67], v[32:47]
	ds_read_b64_tr_b16 v[86:87], v247 offset:25792
	ds_read_b64_tr_b16 v[88:89], v247 offset:28352
	ds_read_b64_tr_b16 v[90:91], v247 offset:30912
	ds_read_b64_tr_b16 v[92:93], v247 offset:33472
	ds_read_b64_tr_b16 v[248:249], v247 offset:36032
	ds_read_b64_tr_b16 v[250:251], v247 offset:38592
	ds_read_b64_tr_b16 v[80:81], v247 offset:41152
	ds_read_b64_tr_b16 v[82:83], v247 offset:43712
	s_waitcnt lgkmcnt(14)
	v_mfma_f32_32x32x16_bf16 v[16:31], v[164:167], v[76:79], v[16:31]
	s_waitcnt lgkmcnt(6)
	v_mfma_f32_32x32x16_bf16 v[0:15], v[86:89], v[76:79], v[0:15]
	v_mfma_f32_32x32x16_bf16 v[16:31], v[168:171], v[72:75], v[16:31]
	s_waitcnt lgkmcnt(4)
	v_mfma_f32_32x32x16_bf16 v[0:15], v[90:93], v[72:75], v[0:15]
	v_mfma_f32_32x32x16_bf16 v[16:31], v[172:175], v[68:71], v[16:31]
	s_waitcnt lgkmcnt(2)
	v_mfma_f32_32x32x16_bf16 v[0:15], v[248:251], v[68:71], v[0:15]
	v_mfma_f32_32x32x16_bf16 v[16:31], v[176:179], v[64:67], v[16:31]
	s_waitcnt lgkmcnt(0)
	v_mfma_f32_32x32x16_bf16 v[0:15], v[80:83], v[64:67], v[0:15]
	s_cbranch_scc1 .LBB0_636
	v_mov_b32_e32 v229, v84
	v_mov_b32_e32 v182, v246
	s_branch .LBB0_642
; #define LAS __attribute__((address_space(3)))
; __device__ __forceinline__ void attn_phase(const Params& p, LAS unsigned char* lds) {
;     ...
;                 LAS unsigned char* Ks = lds + (jt & 1) * ABUF; LAS unsigned char* Vs = Ks + KBUF;
;                 { LAS unsigned char* kd = Ks + srow * KS_STRIDE + ssub * 16; LAS unsigned char* vd = Vs + srow * VS_STRIDE + ssub * 16;
;                   *(LAS u32x4*)(kd) = kreg[0]; *(LAS u32x4*)(kd + 128) = kreg[1]; *(LAS u32x4*)(kd + 256) = kreg[2]; *(LAS u32x4*)(vd) = vreg[0]; *(LAS u32x4*)(vd + 128) = vreg[1]; }
;                 __syncthreads();
;                 if (jt + 1 < ntiles) LOAD_TILE(jt + 1);
.Lat1_entry:
	s_mov_b32 s100, 0
.Lat1_loop:
	s_add_i32 s54, s8, -1
	s_bitcmp1_b32 s54, 0
	s_cselect_b32 s16, 0xb400, 0
	s_add_i32 s55, s16, 0
	v_add3_u32 v164, s55, v185, v190
	s_cmp_ge_u32 s8, s51
	v_add3_u32 v165, s55, v236, v190
	s_waitcnt vmcnt(4)
	ds_write_b128 v164, v[148:151]
	s_waitcnt vmcnt(3)
	ds_write_b128 v164, v[152:155] offset:128
	s_waitcnt vmcnt(2)
	ds_write_b128 v164, v[156:159] offset:256
	s_waitcnt vmcnt(1)
	ds_write_b128 v165, v[144:147] offset:25600
	s_waitcnt vmcnt(0)
	ds_write_b128 v165, v[160:163] offset:25728
	s_waitcnt lgkmcnt(0)
	s_barrier
	s_cbranch_scc1 .Lat1_646
	v_mov_b32_e32 v159, 0
	v_mov_b32_e32 v158, 0
	v_mov_b32_e32 v157, 0
	v_mov_b32_e32 v156, 0
	v_mov_b32_e32 v155, 0
	v_mov_b32_e32 v154, 0
	v_mov_b32_e32 v153, 0
	v_mov_b32_e32 v152, 0
	v_mov_b32_e32 v151, 0
	v_mov_b32_e32 v150, 0
	v_mov_b32_e32 v149, 0
	v_mov_b32_e32 v148, 0
	v_mov_b32_e32 v163, 0
	v_mov_b32_e32 v162, 0
	v_mov_b32_e32 v161, 0
	v_mov_b32_e32 v160, 0
	v_mov_b32_e32 v147, 0
	v_mov_b32_e32 v146, 0
	v_mov_b32_e32 v145, 0
	v_mov_b32_e32 v144, 0
	s_and_saveexec_b64 s[44:45], s[4:5]
	s_cbranch_execz .Lat1_645
	v_lshl_add_u64 v[164:165], s[28:29], 0, v[230:231]
	v_add_co_u32_e32 v166, vcc, 0x3020000, v164
	s_nop 1
	v_addc_co_u32_e32 v167, vcc, 0, v165, vcc
	global_load_dwordx4 v[148:151], v[166:167], off
	global_load_dwordx4 v[152:155], v[166:167], off offset:128
	v_lshl_add_u64 v[166:167], s[28:29], 0, v[232:233]
	v_add_co_u32_e32 v164, vcc, 0x2b520000, v164
	s_nop 1
	v_addc_co_u32_e32 v165, vcc, 0, v165, vcc
	global_load_dwordx4 v[156:159], v[166:167], off
	global_load_dwordx4 v[144:147], v[164:165], off
	global_load_dwordx4 v[160:163], v[164:165], off offset:128

; #define LAS __attribute__((address_space(3)))
; __device__ __forceinline__ s16x4 vtr(const LAS unsigned char* ptr) { return __builtin_bit_cast(s16x4, __builtin_amdgcn_ds_read_tr16_b64_v4i16((LAS v4i16_t*)ptr)); }
; __device__ __forceinline__ void attn_phase(const Params& p, LAS unsigned char* lds) {
;     ...
;                 const LAS unsigned char* vb = Vs + (4 * hi + ((lane & 15) >> 2)) * VS_STRIDE + (((lane >> 4) & 1) * 16 + 4 * (lane & 3)) * 2;
;                 s16x4 vlo[2][4], vhi[2][4];
; #pragma unroll
;                 for (int s = 0; s < 4; ++s) { vlo[0][s] = vtr(vb + (16 * s) * VS_STRIDE); vhi[0][s] = vtr(vb + (16 * s + 8) * VS_STRIDE); }
.Lat1_646:
	s_cmp_eq_u32 s100, 0
	s_cbranch_scc1 .Lat1_qk
	s_xor_b32 s101, s55, 0xb400
	v_add_u32_e32 v164, s101, v239
	v_add_u32_e32 v247, v164, v240
	ds_read_b64_tr_b16 v[174:175], v247 offset:33280
	ds_read_b64_tr_b16 v[168:169], v247 offset:35840
	ds_read_b64_tr_b16 v[170:171], v247 offset:38400
	ds_read_b64_tr_b16 v[164:165], v247 offset:40960
	ds_read_b64_tr_b16 v[176:177], v247 offset:25600
	ds_read_b64_tr_b16 v[178:179], v247 offset:28160
	ds_read_b64_tr_b16 v[172:173], v247 offset:30720
	ds_read_b64_tr_b16 v[166:167], v247 offset:43520

; __device__ __forceinline__ unsigned cvtpk(float lo, float hi) { return pg8::cvt_pk_bf16(lo, hi); }
; __device__ __forceinline__ s16x4 vtr(const LAS unsigned char* ptr) { return __builtin_bit_cast(s16x4, __builtin_amdgcn_ds_read_tr16_b64_v4i16((LAS v4i16_t*)ptr)); }
; __device__ __forceinline__ void attn_phase(const Params& p, LAS unsigned char* lds) {
;     ...
;                 const float mn = fmaxf(mrun, rm), alpha = __builtin_amdgcn_exp2f(mrun - mn); mrun = mn;
;                 float ps = 0.f;
; #pragma unroll
;                 for (int r = 0; r < 16; ++r) { p0[r] = __builtin_amdgcn_exp2f(p0[r] - mn); p1[r] = __builtin_amdgcn_exp2f(p1[r] - mn); ps += p0[r] + p1[r]; }
;                 lrun = lrun * alpha + ps;
;                 if (__any(alpha != 1.0f)) {
; #pragma unroll
;                     for (int d = 0; d < 4; ++d) o[d] *= alpha; }
;                 bf16x8 pf[4];
; #pragma unroll
;                 for (int s = 0; s < 2; ++s) {
;                     u32x4 w0 = {cvtpk(p0[8 * s + 0], p0[8 * s + 1]), cvtpk(p0[8 * s + 2], p0[8 * s + 3]), cvtpk(p0[8 * s + 4], p0[8 * s + 5]), cvtpk(p0[8 * s + 6], p0[8 * s + 7])};
;                     u32x4 w1 = {cvtpk(p1[8 * s + 0], p1[8 * s + 1]), cvtpk(p1[8 * s + 2], p1[8 * s + 3]), cvtpk(p1[8 * s + 4], p1[8 * s + 5]), cvtpk(p1[8 * s + 6], p1[8 * s + 7])};
;                     pf[s] = __builtin_bit_cast(bf16x8, w0); pf[2 + s] = __builtin_bit_cast(bf16x8, w1); }
; #pragma unroll
;                 for (int d = 0; d < 4; ++d) {
;                     if (d < 3) {
; #pragma unroll
;                         for (int s = 0; s < 4; ++s) { vlo[(d + 1) & 1][s] = vtr(vb + (16 * s) * VS_STRIDE + (d + 1) * 64); vhi[(d + 1) & 1][s] = vtr(vb + (16 * s + 8) * VS_STRIDE + (d + 1) * 64); } }
; #pragma unroll
;                     for (int s = 0; s < 4; ++s) {
;                         const s16x4 lo = vlo[d & 1][s], hh = vhi[d & 1][s];
;                         const bf16x8 vf = {lo[0], lo[1], lo[2], lo[3], hh[0], hh[1], hh[2], hh[3]};
;                         o[d] = __builtin_amdgcn_mfma_f32_32x32x16_bf16(vf, pf[s], o[d], 0, 0, 0); } }
.Lat1_650:
	v_sub_f32_e32 v64, v64, v246
	v_sub_f32_e32 v80, v80, v246
	v_exp_f32_e32 v64, v64
	v_exp_f32_e32 v80, v80
	v_sub_f32_e32 v65, v65, v246
	v_sub_f32_e32 v81, v81, v246
	v_exp_f32_e32 v65, v65
	v_exp_f32_e32 v81, v81
	v_sub_f32_e32 v66, v66, v246
	v_sub_f32_e32 v82, v82, v246
	v_exp_f32_e32 v66, v66
	v_exp_f32_e32 v82, v82
	v_sub_f32_e32 v67, v67, v246
	v_sub_f32_e32 v83, v83, v246
	v_exp_f32_e32 v67, v67
	v_exp_f32_e32 v83, v83
	v_add_f32_e32 v248, v64, v80
	v_add_f32_e32 v248, 0, v248
	v_add_f32_e32 v249, v65, v81
	v_add_f32_e32 v248, v249, v248
	v_add_f32_e32 v249, v66, v82
	v_add_f32_e32 v248, v249, v248
	v_add_f32_e32 v249, v67, v83
	v_sub_f32_e32 v68, v68, v246
	v_sub_f32_e32 v84, v84, v246
	v_add_f32_e32 v248, v249, v248
	v_exp_f32_e32 v68, v68
	v_exp_f32_e32 v249, v84
	v_sub_f32_e32 v69, v69, v246
	v_sub_f32_e32 v85, v85, v246
	v_exp_f32_e32 v69, v69
	v_exp_f32_e32 v85, v85
	v_sub_f32_e32 v70, v70, v246
	v_sub_f32_e32 v86, v86, v246
	v_exp_f32_e32 v70, v70
	v_exp_f32_e32 v86, v86
	v_sub_f32_e32 v71, v71, v246
	v_sub_f32_e32 v87, v87, v246
	v_exp_f32_e32 v71, v71
	v_exp_f32_e32 v87, v87
	v_sub_f32_e32 v72, v72, v246
	v_sub_f32_e32 v88, v88, v246
	v_add_f32_e32 v84, v68, v249
	v_exp_f32_e32 v72, v72
	v_exp_f32_e32 v88, v88
	v_sub_f32_e32 v73, v73, v246
	v_sub_f32_e32 v89, v89, v246
	v_add_f32_e32 v84, v84, v248
	v_add_f32_e32 v248, v69, v85
	v_exp_f32_e32 v73, v73
	v_exp_f32_e32 v89, v89
	v_sub_f32_e32 v74, v74, v246
	v_sub_f32_e32 v90, v90, v246
	v_add_f32_e32 v84, v248, v84
	v_add_f32_e32 v248, v70, v86
	v_exp_f32_e32 v74, v74
	v_exp_f32_e32 v90, v90
	v_sub_f32_e32 v75, v75, v246
	v_sub_f32_e32 v91, v91, v246
	v_add_f32_e32 v84, v248, v84
	v_add_f32_e32 v248, v71, v87
	v_exp_f32_e32 v75, v75
	v_exp_f32_e32 v91, v91
	v_add_f32_e32 v84, v248, v84
	v_add_f32_e32 v248, v72, v88
	v_add_f32_e32 v84, v248, v84
	v_add_f32_e32 v248, v73, v89
	v_add_f32_e32 v84, v248, v84
	v_add_f32_e32 v248, v74, v90
	v_add_f32_e32 v84, v248, v84
	v_add_f32_e32 v248, v75, v91
	v_sub_f32_e32 v76, v76, v246
	v_add_f32_e32 v84, v248, v84
	v_exp_f32_e32 v248, v76
	v_sub_f32_e32 v76, v92, v246
	v_sub_f32_e32 v77, v77, v246
	v_exp_f32_e32 v92, v76
	v_exp_f32_e32 v250, v77
	v_sub_f32_e32 v77, v93, v246
	v_exp_f32_e32 v93, v77
	v_add_f32_e32 v76, v248, v92
	v_add_f32_e32 v76, v76, v84
	v_cvt_pk_bf16_f32 v72, v72, v73
	v_add_f32_e32 v77, v250, v93
	v_add_f32_e32 v76, v77, v76
	v_sub_f32_e32 v77, v78, v246
	v_exp_f32_e32 v251, v77
	v_sub_f32_e32 v77, v94, v246
	v_exp_f32_e32 v94, v77
	v_cvt_pk_bf16_f32 v78, v68, v69
	v_cvt_pk_bf16_f32 v68, v80, v81
	v_cvt_pk_bf16_f32 v69, v82, v83
	v_add_f32_e32 v77, v251, v94
	v_add_f32_e32 v76, v77, v76
	v_sub_f32_e32 v77, v79, v246
	v_exp_f32_e32 v252, v77
	v_sub_f32_e32 v77, v95, v246
	v_exp_f32_e32 v95, v77
	v_cvt_pk_bf16_f32 v79, v70, v71
	v_cvt_pk_bf16_f32 v70, v249, v85
	v_cvt_pk_bf16_f32 v71, v86, v87
	v_add_f32_e32 v77, v252, v95
	v_add_f32_e32 v84, v77, v76
	v_cvt_pk_bf16_f32 v76, v64, v65
	v_cvt_pk_bf16_f32 v77, v66, v67
	v_cvt_pk_bf16_f32 v73, v74, v75
	v_cvt_pk_bf16_f32 v74, v248, v250
	v_cvt_pk_bf16_f32 v75, v251, v252
	v_cvt_pk_bf16_f32 v64, v88, v89
	v_cvt_pk_bf16_f32 v65, v90, v91
	v_cvt_pk_bf16_f32 v66, v92, v93
	ds_read_b64_tr_b16 v[80:81], v247 offset:25664
	ds_read_b64_tr_b16 v[82:83], v247 offset:28224
	ds_read_b64_tr_b16 v[86:87], v247 offset:30784
	ds_read_b64_tr_b16 v[88:89], v247 offset:33344
	ds_read_b64_tr_b16 v[90:91], v247 offset:35904
	ds_read_b64_tr_b16 v[92:93], v247 offset:38464
	ds_read_b64_tr_b16 v[248:249], v247 offset:41024
	ds_read_b64_tr_b16 v[250:251], v247 offset:43584
	v_mfma_f32_32x32x16_bf16 v[48:63], v[176:179], v[76:79], v[48:63]
	v_cvt_pk_bf16_f32 v67, v94, v95
	v_fmac_f32_e32 v84, v229, v182
	s_waitcnt lgkmcnt(6)
	v_mfma_f32_32x32x16_bf16 v[32:47], v[80:83], v[76:79], v[32:47]
	v_mfma_f32_32x32x16_bf16 v[48:63], v[172:175], v[72:75], v[48:63]
	s_waitcnt lgkmcnt(4)
	v_mfma_f32_32x32x16_bf16 v[32:47], v[86:89], v[72:75], v[32:47]
	v_mfma_f32_32x32x16_bf16 v[48:63], v[168:171], v[68:71], v[48:63]
	s_waitcnt lgkmcnt(2)
	v_mfma_f32_32x32x16_bf16 v[32:47], v[90:93], v[68:71], v[32:47]
	v_mfma_f32_32x32x16_bf16 v[48:63], v[164:167], v[64:67], v[48:63]
	ds_read_b64_tr_b16 v[164:165], v247 offset:25728
	ds_read_b64_tr_b16 v[166:167], v247 offset:28288
	ds_read_b64_tr_b16 v[168:169], v247 offset:30848
	ds_read_b64_tr_b16 v[170:171], v247 offset:33408
	ds_read_b64_tr_b16 v[172:173], v247 offset:35968
	ds_read_b64_tr_b16 v[174:175], v247 offset:38528
	ds_read_b64_tr_b16 v[176:177], v247 offset:41088
	ds_read_b64_tr_b16 v[178:179], v247 offset:43648
	s_waitcnt lgkmcnt(8)
	v_mfma_f32_32x32x16_bf16 v[32:47], v[248:251], v[64:67], v[32:47]
	ds_read_b64_tr_b16 v[86:87], v247 offset:25792
	ds_read_b64_tr_b16 v[88:89], v247 offset:28352
	ds_read_b64_tr_b16 v[90:91], v247 offset:30912
	ds_read_b64_tr_b16 v[92:93], v247 offset:33472
	ds_read_b64_tr_b16 v[248:249], v247 offset:36032
	ds_read_b64_tr_b16 v[250:251], v247 offset:38592
	ds_read_b64_tr_b16 v[80:81], v247 offset:41152
	ds_read_b64_tr_b16 v[82:83], v247 offset:43712
	s_waitcnt lgkmcnt(14)
	v_mfma_f32_32x32x16_bf16 v[16:31], v[164:167], v[76:79], v[16:31]
	s_waitcnt lgkmcnt(6)
	v_mfma_f32_32x32x16_bf16 v[0:15], v[86:89], v[76:79], v[0:15]
	v_mfma_f32_32x32x16_bf16 v[16:31], v[168:171], v[72:75], v[16:31]
	s_waitcnt lgkmcnt(4)
	v_mfma_f32_32x32x16_bf16 v[0:15], v[90:93], v[72:75], v[0:15]
	v_mfma_f32_32x32x16_bf16 v[16:31], v[172:175], v[68:71], v[16:31]
	s_waitcnt lgkmcnt(2)
	v_mfma_f32_32x32x16_bf16 v[0:15], v[248:251], v[68:71], v[0:15]
	v_mfma_f32_32x32x16_bf16 v[16:31], v[176:179], v[64:67], v[16:31]
	s_waitcnt lgkmcnt(0)
	v_mfma_f32_32x32x16_bf16 v[0:15], v[80:83], v[64:67], v[0:15]
	v_mov_b32_e32 v229, v84
	v_mov_b32_e32 v182, v246
; #define LAS __attribute__((address_space(3)))
; __device__ __forceinline__ int crow(int r, int hi) { return (r & 3) + 8 * (r >> 2) + 4 * hi; }
; __device__ __forceinline__ s16x4 vtr(const LAS unsigned char* ptr) { return __builtin_bit_cast(s16x4, __builtin_amdgcn_ds_read_tr16_b64_v4i16((LAS v4i16_t*)ptr)); }
; __device__ __forceinline__ void attn_phase(const Params& p, LAS unsigned char* lds) {
;     ...
;                 f32x16 p0 = (f32x16){}, p1 = (f32x16){};
;                 { const LAS unsigned char* kp = Ks + c * KS_STRIDE + hi * 16;
;                   bf16x8 a0 = *(const LAS bf16x8*)(kp), a1 = *(const LAS bf16x8*)(kp + 32 * KS_STRIDE);
; #pragma unroll
;                   for (int d = 0; d < 12; ++d) { bf16x8 n0 = a0, n1 = a1;
;                       if (d < 11) { n0 = *(const LAS bf16x8*)(kp + (d + 1) * 32); n1 = *(const LAS bf16x8*)(kp + 32 * KS_STRIDE + (d + 1) * 32); }
;                       p0 = __builtin_amdgcn_mfma_f32_32x32x16_bf16(a0, qf[d], p0, 0, 0, 0); p1 = __builtin_amdgcn_mfma_f32_32x32x16_bf16(a1, qf[d], p1, 0, 0, 0);
;                       a0 = n0; a1 = n1; } }
;                 const LAS unsigned char* vb = Vs + (4 * hi + ((lane & 15) >> 2)) * VS_STRIDE + (((lane >> 4) & 1) * 16 + 4 * (lane & 3)) * 2;
;                 s16x4 vlo[2][4], vhi[2][4];
; #pragma unroll
;                 for (int s = 0; s < 4; ++s) { vlo[0][s] = vtr(vb + (16 * s) * VS_STRIDE); vhi[0][s] = vtr(vb + (16 * s + 8) * VS_STRIDE); }
;                 if (jt == 0) {
; #pragma unroll
;                     for (int r = 0; r < 16; ++r) { if (crow(r, hi) >= NMETA) p0[r] = NEG; p1[r] = NEG; }
;                 } else if (jt - 1 >= 4 * qblk) {
;                     const int kb = 64 * (jt - 1);
; #pragma unroll
;                     for (int r = 0; r < 16; ++r) { const int key = kb + crow(r, hi); if (key > tq) p0[r] = NEG; if (key + 32 > tq) p1[r] = NEG; }
;                 }
.Lat1_qk:
	s_barrier
	v_add3_u32 v176, s55, v237, v184
	ds_read_b128 v[64:67], v176
	ds_read_b128 v[164:167], v176 offset:32
	ds_read_b128 v[80:83], v176 offset:12800
	ds_read_b128 v[168:171], v176 offset:12832
	s_cmp_le_u32 s54, s50
	s_waitcnt lgkmcnt(3)
	v_mfma_f32_32x32x16_bf16 v[64:79], v[64:67], v[96:99], 0
	s_waitcnt lgkmcnt(1)
	v_mfma_f32_32x32x16_bf16 v[80:95], v[80:83], v[96:99], 0
	v_mfma_f32_32x32x16_bf16 v[64:79], v[164:167], v[100:103], v[64:79]
	s_waitcnt lgkmcnt(0)
	v_mfma_f32_32x32x16_bf16 v[80:95], v[168:171], v[100:103], v[80:95]
	ds_read_b128 v[164:167], v176 offset:64
	ds_read_b128 v[168:171], v176 offset:96
	s_waitcnt lgkmcnt(1)
	v_mfma_f32_32x32x16_bf16 v[64:79], v[164:167], v[104:107], v[64:79]
	ds_read_b128 v[164:167], v176 offset:12864
	ds_read_b128 v[172:175], v176 offset:12896
	s_waitcnt lgkmcnt(1)
	v_mfma_f32_32x32x16_bf16 v[80:95], v[164:167], v[104:107], v[80:95]
	v_mfma_f32_32x32x16_bf16 v[64:79], v[168:171], v[108:111], v[64:79]
	ds_read_b128 v[164:167], v176 offset:128
	ds_read_b128 v[168:171], v176 offset:160
	s_waitcnt lgkmcnt(2)
	v_mfma_f32_32x32x16_bf16 v[80:95], v[172:175], v[108:111], v[80:95]
	s_waitcnt lgkmcnt(1)
	v_mfma_f32_32x32x16_bf16 v[64:79], v[164:167], v[112:115], v[64:79]
	ds_read_b128 v[164:167], v176 offset:12928
	ds_read_b128 v[172:175], v176 offset:12960
	s_waitcnt lgkmcnt(1)
	v_mfma_f32_32x32x16_bf16 v[80:95], v[164:167], v[112:115], v[80:95]
	v_mfma_f32_32x32x16_bf16 v[64:79], v[168:171], v[116:119], v[64:79]
	ds_read_b128 v[164:167], v176 offset:192
	ds_read_b128 v[168:171], v176 offset:224
	s_waitcnt lgkmcnt(2)
	v_mfma_f32_32x32x16_bf16 v[80:95], v[172:175], v[116:119], v[80:95]
	s_waitcnt lgkmcnt(1)
	v_mfma_f32_32x32x16_bf16 v[64:79], v[164:167], v[120:123], v[64:79]
	ds_read_b128 v[164:167], v176 offset:12992
	ds_read_b128 v[172:175], v176 offset:13024
	s_waitcnt lgkmcnt(1)
	v_mfma_f32_32x32x16_bf16 v[80:95], v[164:167], v[120:123], v[80:95]
	v_mfma_f32_32x32x16_bf16 v[64:79], v[168:171], v[124:127], v[64:79]
	ds_read_b128 v[164:167], v176 offset:256
	ds_read_b128 v[168:171], v176 offset:288
	s_waitcnt lgkmcnt(2)
	v_mfma_f32_32x32x16_bf16 v[80:95], v[172:175], v[124:127], v[80:95]
	s_waitcnt lgkmcnt(1)
	v_mfma_f32_32x32x16_bf16 v[64:79], v[164:167], v[128:131], v[64:79]
	ds_read_b128 v[164:167], v176 offset:13056
	ds_read_b128 v[172:175], v176 offset:13088
	s_waitcnt lgkmcnt(1)
	v_mfma_f32_32x32x16_bf16 v[80:95], v[164:167], v[128:131], v[80:95]
	v_mfma_f32_32x32x16_bf16 v[64:79], v[168:171], v[132:135], v[64:79]
	ds_read_b128 v[164:167], v176 offset:320
	ds_read_b128 v[168:171], v176 offset:352
	s_waitcnt lgkmcnt(2)
	v_mfma_f32_32x32x16_bf16 v[80:95], v[172:175], v[132:135], v[80:95]
	s_waitcnt lgkmcnt(1)
	v_mfma_f32_32x32x16_bf16 v[64:79], v[164:167], v[136:139], v[64:79]
	ds_read_b128 v[164:167], v176 offset:13120
	ds_read_b128 v[248:251], v176 offset:13152
	s_waitcnt lgkmcnt(1)
	v_mfma_f32_32x32x16_bf16 v[80:95], v[164:167], v[136:139], v[80:95]
	v_mfma_f32_32x32x16_bf16 v[64:79], v[168:171], v[140:143], v[64:79]
	s_waitcnt lgkmcnt(0)
	v_mfma_f32_32x32x16_bf16 v[80:95], v[248:251], v[140:143], v[80:95]
	s_cbranch_scc1 .Lat1_nomask
	v_add_u32_e32 v246, s53, v238
	v_add_u32_e32 v248, 32, v246
	v_cmp_le_i32_e32 vcc, v248, v228
	v_add_u32_e32 v248, 33, v246
	s_nop 6
	v_cndmask_b32_e32 v80, v245, v80, vcc
	v_cmp_lt_i32_e32 vcc, v246, v228
	s_nop 1
	v_cndmask_b32_e32 v65, v245, v65, vcc
	v_cmp_le_i32_e32 vcc, v246, v228
	s_nop 1
	v_cndmask_b32_e32 v64, v245, v64, vcc
	v_cmp_le_i32_e32 vcc, v248, v228
	v_add_u32_e32 v248, 2, v246
	s_nop 0
	v_cndmask_b32_e32 v81, v245, v81, vcc
	v_cmp_le_i32_e32 vcc, v248, v228
	v_add_u32_e32 v248, 34, v246
	s_nop 0
	v_cndmask_b32_e32 v66, v245, v66, vcc
	v_cmp_le_i32_e32 vcc, v248, v228
	v_add_u32_e32 v248, 3, v246
	s_nop 0
	v_cndmask_b32_e32 v82, v245, v82, vcc
	v_cmp_le_i32_e32 vcc, v248, v228
	v_add_u32_e32 v248, 35, v246
	s_nop 0
	v_cndmask_b32_e32 v67, v245, v67, vcc
	v_cmp_le_i32_e32 vcc, v248, v228
	v_add_u32_e32 v248, 8, v246
	s_nop 0
	v_cndmask_b32_e32 v83, v245, v83, vcc
	v_cmp_le_i32_e32 vcc, v248, v228
	v_add_u32_e32 v248, 40, v246
	s_nop 0
	v_cndmask_b32_e32 v68, v245, v68, vcc
	v_cmp_le_i32_e32 vcc, v248, v228
	v_add_u32_e32 v248, 9, v246
	s_nop 0
	v_cndmask_b32_e32 v84, v245, v84, vcc
	v_cmp_le_i32_e32 vcc, v248, v228
	v_add_u32_e32 v248, 41, v246
	s_nop 0
	v_cndmask_b32_e32 v69, v245, v69, vcc
	v_cmp_le_i32_e32 vcc, v248, v228
	v_add_u32_e32 v248, 10, v246
	s_nop 0
	v_cndmask_b32_e32 v85, v245, v85, vcc
	v_cmp_le_i32_e32 vcc, v248, v228
	v_add_u32_e32 v248, 42, v246
	s_nop 0
	v_cndmask_b32_e32 v70, v245, v70, vcc
	v_cmp_le_i32_e32 vcc, v248, v228
	v_add_u32_e32 v248, 11, v246
	s_nop 0
	v_cndmask_b32_e32 v86, v245, v86, vcc
	v_cmp_le_i32_e32 vcc, v248, v228
	v_add_u32_e32 v248, 43, v246
	s_nop 0
	v_cndmask_b32_e32 v71, v245, v71, vcc
	v_cmp_le_i32_e32 vcc, v248, v228
	v_add_u32_e32 v248, 16, v246
	s_nop 0
	v_cndmask_b32_e32 v87, v245, v87, vcc
	v_cmp_le_i32_e32 vcc, v248, v228
	v_add_u32_e32 v248, 48, v246
	s_nop 0
	v_cndmask_b32_e32 v72, v245, v72, vcc
	v_cmp_le_i32_e32 vcc, v248, v228
	v_add_u32_e32 v248, 17, v246
	s_nop 0
	v_cndmask_b32_e32 v88, v245, v88, vcc
	v_cmp_le_i32_e32 vcc, v248, v228
	v_add_u32_e32 v248, 49, v246
	s_nop 0
	v_cndmask_b32_e32 v73, v245, v73, vcc
	v_cmp_le_i32_e32 vcc, v248, v228
	v_add_u32_e32 v248, 18, v246
	s_nop 0
	v_cndmask_b32_e32 v89, v245, v89, vcc
	v_cmp_le_i32_e32 vcc, v248, v228
	v_add_u32_e32 v248, 50, v246
	s_nop 0
	v_cndmask_b32_e32 v74, v245, v74, vcc
	v_cmp_le_i32_e32 vcc, v248, v228
	v_add_u32_e32 v248, 19, v246
	s_nop 0
	v_cndmask_b32_e32 v90, v245, v90, vcc
	v_cmp_le_i32_e32 vcc, v248, v228
	v_add_u32_e32 v248, 51, v246
	s_nop 0
	v_cndmask_b32_e32 v75, v245, v75, vcc
	v_cmp_le_i32_e32 vcc, v248, v228
	v_add_u32_e32 v248, 24, v246
	s_nop 0
	v_cndmask_b32_e32 v91, v245, v91, vcc
	v_cmp_le_i32_e32 vcc, v248, v228
	v_add_u32_e32 v248, 56, v246
	s_nop 0
	v_cndmask_b32_e32 v76, v245, v76, vcc
	v_cmp_le_i32_e32 vcc, v248, v228
	v_add_u32_e32 v248, 25, v246
	s_nop 0
	v_cndmask_b32_e32 v92, v245, v92, vcc
	v_cmp_le_i32_e32 vcc, v248, v228
	v_add_u32_e32 v248, 57, v246
	s_nop 0
	v_cndmask_b32_e32 v77, v245, v77, vcc
	v_cmp_le_i32_e32 vcc, v248, v228
	v_add_u32_e32 v248, 26, v246
	s_nop 0
	v_cndmask_b32_e32 v93, v245, v93, vcc
	v_cmp_le_i32_e32 vcc, v248, v228
	v_add_u32_e32 v248, 58, v246
	s_nop 0
	v_cndmask_b32_e32 v78, v245, v78, vcc
	v_cmp_le_i32_e32 vcc, v248, v228
	v_add_u32_e32 v248, 27, v246
	v_add_u32_e32 v246, 59, v246
	v_cndmask_b32_e32 v94, v245, v94, vcc
	v_cmp_le_i32_e32 vcc, v248, v228
	s_nop 1
	v_cndmask_b32_e32 v79, v245, v79, vcc
	v_cmp_le_i32_e32 vcc, v246, v228
	s_nop 1
	v_cndmask_b32_e32 v95, v245, v95, vcc
; #define LAS __attribute__((address_space(3)))
; __device__ __forceinline__ s16x4 vtr(const LAS unsigned char* ptr) { return __builtin_bit_cast(s16x4, __builtin_amdgcn_ds_read_tr16_b64_v4i16((LAS v4i16_t*)ptr)); }
; __device__ __forceinline__ void attn_phase(const Params& p, LAS unsigned char* lds) {
;     ...
;             for (int jt = 0; jt < ntiles; ++jt) {
;                 LAS unsigned char* Ks = lds + (jt & 1) * ABUF; LAS unsigned char* Vs = Ks + KBUF;
;                 { LAS unsigned char* kd = Ks + srow * KS_STRIDE + ssub * 16; LAS unsigned char* vd = Vs + srow * VS_STRIDE + ssub * 16;
;                   *(LAS u32x4*)(kd) = kreg[0]; *(LAS u32x4*)(kd + 128) = kreg[1]; *(LAS u32x4*)(kd + 256) = kreg[2]; *(LAS u32x4*)(vd) = vreg[0]; *(LAS u32x4*)(vd + 128) = vreg[1]; }
;                 __syncthreads();
;                 if (jt + 1 < ntiles) LOAD_TILE(jt + 1);
;     ...
;                 const LAS unsigned char* vb = Vs + (4 * hi + ((lane & 15) >> 2)) * VS_STRIDE + (((lane >> 4) & 1) * 16 + 4 * (lane & 3)) * 2;
;                 s16x4 vlo[2][4], vhi[2][4];
; #pragma unroll
;                 for (int s = 0; s < 4; ++s) { vlo[0][s] = vtr(vb + (16 * s) * VS_STRIDE); vhi[0][s] = vtr(vb + (16 * s + 8) * VS_STRIDE); }
.Lat1_nomask:
	s_add_i32 s53, s53, 64
	s_add_i32 s8, s8, 1
	v_lshl_add_u64 v[232:233], v[232:233], 0, s[10:11]
	v_lshl_add_u64 v[230:231], v[230:231], 0, s[12:13]
	s_mov_b32 s100, 1
	s_cmp_eq_u32 s52, s53
	s_cbranch_scc0 .Lat1_loop
	v_add_u32_e32 v164, s55, v239
	v_add_u32_e32 v247, v164, v240
	ds_read_b64_tr_b16 v[174:175], v247 offset:33280
	ds_read_b64_tr_b16 v[168:169], v247 offset:35840
	ds_read_b64_tr_b16 v[170:171], v247 offset:38400
	ds_read_b64_tr_b16 v[164:165], v247 offset:40960
	ds_read_b64_tr_b16 v[176:177], v247 offset:25600
	ds_read_b64_tr_b16 v[178:179], v247 offset:28160
	ds_read_b64_tr_b16 v[172:173], v247 offset:30720
	ds_read_b64_tr_b16 v[166:167], v247 offset:43520

; __device__ __forceinline__ unsigned cvtpk(float lo, float hi) { return pg8::cvt_pk_bf16(lo, hi); }
; __device__ __forceinline__ s16x4 vtr(const LAS unsigned char* ptr) { return __builtin_bit_cast(s16x4, __builtin_amdgcn_ds_read_tr16_b64_v4i16((LAS v4i16_t*)ptr)); }
; __device__ __forceinline__ void attn_phase(const Params& p, LAS unsigned char* lds) {
;     ...
;                 const float mn = fmaxf(mrun, rm), alpha = __builtin_amdgcn_exp2f(mrun - mn); mrun = mn;
;                 float ps = 0.f;
; #pragma unroll
;                 for (int r = 0; r < 16; ++r) { p0[r] = __builtin_amdgcn_exp2f(p0[r] - mn); p1[r] = __builtin_amdgcn_exp2f(p1[r] - mn); ps += p0[r] + p1[r]; }
;                 lrun = lrun * alpha + ps;
;                 if (__any(alpha != 1.0f)) {
; #pragma unroll
;                     for (int d = 0; d < 4; ++d) o[d] *= alpha; }
;                 bf16x8 pf[4];
; #pragma unroll
;                 for (int s = 0; s < 2; ++s) {
;                     u32x4 w0 = {cvtpk(p0[8 * s + 0], p0[8 * s + 1]), cvtpk(p0[8 * s + 2], p0[8 * s + 3]), cvtpk(p0[8 * s + 4], p0[8 * s + 5]), cvtpk(p0[8 * s + 6], p0[8 * s + 7])};
;                     u32x4 w1 = {cvtpk(p1[8 * s + 0], p1[8 * s + 1]), cvtpk(p1[8 * s + 2], p1[8 * s + 3]), cvtpk(p1[8 * s + 4], p1[8 * s + 5]), cvtpk(p1[8 * s + 6], p1[8 * s + 7])};
;                     pf[s] = __builtin_bit_cast(bf16x8, w0); pf[2 + s] = __builtin_bit_cast(bf16x8, w1); }
; #pragma unroll
;                 for (int d = 0; d < 4; ++d) {
;                     if (d < 3) {
; #pragma unroll
;                         for (int s = 0; s < 4; ++s) { vlo[(d + 1) & 1][s] = vtr(vb + (16 * s) * VS_STRIDE + (d + 1) * 64); vhi[(d + 1) & 1][s] = vtr(vb + (16 * s + 8) * VS_STRIDE + (d + 1) * 64); } }
; #pragma unroll
;                     for (int s = 0; s < 4; ++s) {
;                         const s16x4 lo = vlo[d & 1][s], hh = vhi[d & 1][s];
;                         const bf16x8 vf = {lo[0], lo[1], lo[2], lo[3], hh[0], hh[1], hh[2], hh[3]};
;                         o[d] = __builtin_amdgcn_mfma_f32_32x32x16_bf16(vf, pf[s], o[d], 0, 0, 0); } }
.Lat1e_650:
	v_sub_f32_e32 v64, v64, v246
	v_sub_f32_e32 v80, v80, v246
	v_exp_f32_e32 v64, v64
	v_exp_f32_e32 v80, v80
	v_sub_f32_e32 v65, v65, v246
	v_sub_f32_e32 v81, v81, v246
	v_exp_f32_e32 v65, v65
	v_exp_f32_e32 v81, v81
	v_sub_f32_e32 v66, v66, v246
	v_sub_f32_e32 v82, v82, v246
	v_exp_f32_e32 v66, v66
	v_exp_f32_e32 v82, v82
	v_sub_f32_e32 v67, v67, v246
	v_sub_f32_e32 v83, v83, v246
	v_exp_f32_e32 v67, v67
	v_exp_f32_e32 v83, v83
	v_add_f32_e32 v248, v64, v80
	v_add_f32_e32 v248, 0, v248
	v_add_f32_e32 v249, v65, v81
	v_add_f32_e32 v248, v249, v248
	v_add_f32_e32 v249, v66, v82
	v_add_f32_e32 v248, v249, v248
	v_add_f32_e32 v249, v67, v83
	v_sub_f32_e32 v68, v68, v246
	v_sub_f32_e32 v84, v84, v246
	v_add_f32_e32 v248, v249, v248
	v_exp_f32_e32 v68, v68
	v_exp_f32_e32 v249, v84
	v_sub_f32_e32 v69, v69, v246
	v_sub_f32_e32 v85, v85, v246
	v_exp_f32_e32 v69, v69
	v_exp_f32_e32 v85, v85
	v_sub_f32_e32 v70, v70, v246
	v_sub_f32_e32 v86, v86, v246
	v_exp_f32_e32 v70, v70
	v_exp_f32_e32 v86, v86
	v_sub_f32_e32 v71, v71, v246
	v_sub_f32_e32 v87, v87, v246
	v_exp_f32_e32 v71, v71
	v_exp_f32_e32 v87, v87
	v_sub_f32_e32 v72, v72, v246
	v_sub_f32_e32 v88, v88, v246
	v_add_f32_e32 v84, v68, v249
	v_exp_f32_e32 v72, v72
	v_exp_f32_e32 v88, v88
	v_sub_f32_e32 v73, v73, v246
	v_sub_f32_e32 v89, v89, v246
	v_add_f32_e32 v84, v84, v248
	v_add_f32_e32 v248, v69, v85
	v_exp_f32_e32 v73, v73
	v_exp_f32_e32 v89, v89
	v_sub_f32_e32 v74, v74, v246
	v_sub_f32_e32 v90, v90, v246
	v_add_f32_e32 v84, v248, v84
	v_add_f32_e32 v248, v70, v86
	v_exp_f32_e32 v74, v74
	v_exp_f32_e32 v90, v90
	v_sub_f32_e32 v75, v75, v246
	v_sub_f32_e32 v91, v91, v246
	v_add_f32_e32 v84, v248, v84
	v_add_f32_e32 v248, v71, v87
	v_exp_f32_e32 v75, v75
	v_exp_f32_e32 v91, v91
	v_add_f32_e32 v84, v248, v84
	v_add_f32_e32 v248, v72, v88
	v_add_f32_e32 v84, v248, v84
	v_add_f32_e32 v248, v73, v89
	v_add_f32_e32 v84, v248, v84
	v_add_f32_e32 v248, v74, v90
	v_add_f32_e32 v84, v248, v84
	v_add_f32_e32 v248, v75, v91
	v_sub_f32_e32 v76, v76, v246
	v_add_f32_e32 v84, v248, v84
	v_exp_f32_e32 v248, v76
	v_sub_f32_e32 v76, v92, v246
	v_sub_f32_e32 v77, v77, v246
	v_exp_f32_e32 v92, v76
	v_exp_f32_e32 v250, v77
	v_sub_f32_e32 v77, v93, v246
	v_exp_f32_e32 v93, v77
	v_add_f32_e32 v76, v248, v92
	v_add_f32_e32 v76, v76, v84
	v_cvt_pk_bf16_f32 v72, v72, v73
	v_add_f32_e32 v77, v250, v93
	v_add_f32_e32 v76, v77, v76
	v_sub_f32_e32 v77, v78, v246
	v_exp_f32_e32 v251, v77
	v_sub_f32_e32 v77, v94, v246
	v_exp_f32_e32 v94, v77
	v_cvt_pk_bf16_f32 v78, v68, v69
	v_cvt_pk_bf16_f32 v68, v80, v81
	v_cvt_pk_bf16_f32 v69, v82, v83
	v_add_f32_e32 v77, v251, v94
	v_add_f32_e32 v76, v77, v76
	v_sub_f32_e32 v77, v79, v246
	v_exp_f32_e32 v252, v77
	v_sub_f32_e32 v77, v95, v246
	v_exp_f32_e32 v95, v77
	v_cvt_pk_bf16_f32 v79, v70, v71
	v_cvt_pk_bf16_f32 v70, v249, v85
	v_cvt_pk_bf16_f32 v71, v86, v87
	v_add_f32_e32 v77, v252, v95
	v_add_f32_e32 v84, v77, v76
	v_cvt_pk_bf16_f32 v76, v64, v65
	v_cvt_pk_bf16_f32 v77, v66, v67
	v_cvt_pk_bf16_f32 v73, v74, v75
	v_cvt_pk_bf16_f32 v74, v248, v250
	v_cvt_pk_bf16_f32 v75, v251, v252
	v_cvt_pk_bf16_f32 v64, v88, v89
	v_cvt_pk_bf16_f32 v65, v90, v91
	v_cvt_pk_bf16_f32 v66, v92, v93
	ds_read_b64_tr_b16 v[80:81], v247 offset:25664
	ds_read_b64_tr_b16 v[82:83], v247 offset:28224
	ds_read_b64_tr_b16 v[86:87], v247 offset:30784
	ds_read_b64_tr_b16 v[88:89], v247 offset:33344
	ds_read_b64_tr_b16 v[90:91], v247 offset:35904
	ds_read_b64_tr_b16 v[92:93], v247 offset:38464
	ds_read_b64_tr_b16 v[248:249], v247 offset:41024
	ds_read_b64_tr_b16 v[250:251], v247 offset:43584
	v_mfma_f32_32x32x16_bf16 v[48:63], v[176:179], v[76:79], v[48:63]
	v_cvt_pk_bf16_f32 v67, v94, v95
	v_fmac_f32_e32 v84, v229, v182
	s_waitcnt lgkmcnt(6)
	v_mfma_f32_32x32x16_bf16 v[32:47], v[80:83], v[76:79], v[32:47]
	v_mfma_f32_32x32x16_bf16 v[48:63], v[172:175], v[72:75], v[48:63]
	s_waitcnt lgkmcnt(4)
	v_mfma_f32_32x32x16_bf16 v[32:47], v[86:89], v[72:75], v[32:47]
	v_mfma_f32_32x32x16_bf16 v[48:63], v[168:171], v[68:71], v[48:63]
	s_waitcnt lgkmcnt(2)
	v_mfma_f32_32x32x16_bf16 v[32:47], v[90:93], v[68:71], v[32:47]
	v_mfma_f32_32x32x16_bf16 v[48:63], v[164:167], v[64:67], v[48:63]
	ds_read_b64_tr_b16 v[164:165], v247 offset:25728
	ds_read_b64_tr_b16 v[166:167], v247 offset:28288
	ds_read_b64_tr_b16 v[168:169], v247 offset:30848
	ds_read_b64_tr_b16 v[170:171], v247 offset:33408
	ds_read_b64_tr_b16 v[172:173], v247 offset:35968
	ds_read_b64_tr_b16 v[174:175], v247 offset:38528
	ds_read_b64_tr_b16 v[176:177], v247 offset:41088
	ds_read_b64_tr_b16 v[178:179], v247 offset:43648
	s_waitcnt lgkmcnt(8)
	v_mfma_f32_32x32x16_bf16 v[32:47], v[248:251], v[64:67], v[32:47]
	ds_read_b64_tr_b16 v[86:87], v247 offset:25792
	ds_read_b64_tr_b16 v[88:89], v247 offset:28352
	ds_read_b64_tr_b16 v[90:91], v247 offset:30912
	ds_read_b64_tr_b16 v[92:93], v247 offset:33472
	ds_read_b64_tr_b16 v[248:249], v247 offset:36032
	ds_read_b64_tr_b16 v[250:251], v247 offset:38592
	ds_read_b64_tr_b16 v[80:81], v247 offset:41152
	ds_read_b64_tr_b16 v[82:83], v247 offset:43712
	s_waitcnt lgkmcnt(14)
	v_mfma_f32_32x32x16_bf16 v[16:31], v[164:167], v[76:79], v[16:31]
	s_waitcnt lgkmcnt(6)
	v_mfma_f32_32x32x16_bf16 v[0:15], v[86:89], v[76:79], v[0:15]
	v_mfma_f32_32x32x16_bf16 v[16:31], v[168:171], v[72:75], v[16:31]
	s_waitcnt lgkmcnt(4)
	v_mfma_f32_32x32x16_bf16 v[0:15], v[90:93], v[72:75], v[0:15]
	v_mfma_f32_32x32x16_bf16 v[16:31], v[172:175], v[68:71], v[16:31]
	s_waitcnt lgkmcnt(2)
	v_mfma_f32_32x32x16_bf16 v[0:15], v[248:251], v[68:71], v[0:15]
	v_mfma_f32_32x32x16_bf16 v[16:31], v[176:179], v[64:67], v[16:31]
	s_waitcnt lgkmcnt(0)
	v_mfma_f32_32x32x16_bf16 v[0:15], v[80:83], v[64:67], v[0:15]
	s_branch .LBB0_636
